# LayerNorm third row loop: gain/bias (and shift/scale when modulating) vectors requested at the top of the row ahead of the next-row prefetch; one counted wait instead of eight drains
# baseline (speedup 1.0000x reference)
.LBB0_1909:
	s_waitcnt vmcnt(4)
	v_readlane_b32 s8, v254, 14
	v_readlane_b32 s9, v254, 15
	s_add_u32 s1, s1, s8
	s_addc_u32 s10, s10, s9
	v_readlane_b32 s8, v254, 12
	v_readlane_b32 s9, v254, 13
	s_andn2_b64 vcc, exec, s[12:13]
	s_mov_b32 s26, s11
	v_lshl_add_u64 v[36:37], v[36:37], 0, s[8:9]
	v_readlane_b32 s8, v254, 27
	v_readlane_b32 s9, v254, 28
	v_mov_b32_e32 v47, v12
	v_mov_b32_e32 v21, v13
	v_lshl_add_u64 v[38:39], v[38:39], 0, s[8:9]
	v_mov_b32_e32 v49, v14
	v_mov_b32_e32 v23, v15
	v_mov_b32_e32 v46, v8
	v_mov_b32_e32 v20, v9
	v_mov_b32_e32 v48, v10
	v_mov_b32_e32 v22, v11
	v_mov_b32_e32 v41, v4
	v_mov_b32_e32 v17, v5
	v_mov_b32_e32 v43, v6
	v_mov_b32_e32 v19, v7
	v_mov_b32_e32 v40, v0
	v_mov_b32_e32 v16, v1
	v_mov_b32_e32 v42, v2
	v_mov_b32_e32 v18, v3
	s_cbranch_vccz .LBB0_1939
.LBB0_1910:
	s_add_i32 s11, s26, s82
	s_cmpk_gt_i32 s11, 0x7fff
	s_cselect_b64 s[12:13], -1, 0
	s_cmp_lt_i32 s11, 0x8000
	s_cselect_b32 s14, s11, s26
	s_ashr_i32 s15, s14, 31
	s_lshl_b64 s[14:15], s[14:15], 12
	v_lshl_add_u64 v[0:1], v[28:29], 0, s[14:15]
	global_load_dwordx4 v[164:167], v[30:31], off
	global_load_dwordx4 v[180:183], v[32:33], off
	global_load_dwordx4 v[168:171], v[30:31], off offset:1024
	global_load_dwordx4 v[196:199], v[32:33], off offset:1024
	global_load_dwordx4 v[172:175], v[30:31], off offset:2048
	global_load_dwordx4 v[200:203], v[32:33], off offset:2048
	global_load_dwordx4 v[176:179], v[30:31], off offset:3072
	global_load_dwordx4 v[204:207], v[32:33], off offset:3072
	s_andn2_b64 vcc, exec, s[70:71]
	s_cbranch_vccnz .Llnb_nomod
	s_add_i32 s101, s26, 0xffffc000
	s_lshr_b32 s101, s101, 12
	s_add_i32 s101, s101, 2
	s_ashr_i32 s100, s26, 13
	s_cmpk_lt_i32 s26, 0x4000
	s_cselect_b32 s100, s100, s101
	v_readlane_b32 s101, v255, 2
	s_nop 1
	s_add_i32 s100, s100, s101
	s_mul_i32 s100, s100, 9
	s_ashr_i32 s101, s100, 31
	s_lshl_b64 s[100:101], s[100:101], 12
	v_lshl_add_u64 v[84:85], v[34:35], 0, s[100:101]
	s_mov_b64 s[100:101], 0x1000
	v_lshl_add_u64 v[86:87], v[84:85], 0, s[100:101]
	global_load_dwordx4 v[208:211], v[84:85], off
	global_load_dwordx4 v[224:227], v[86:87], off
	global_load_dwordx4 v[212:215], v[84:85], off offset:1024
	global_load_dwordx4 v[228:231], v[86:87], off offset:1024
	global_load_dwordx4 v[216:219], v[84:85], off offset:2048
	global_load_dwordx4 v[76:79], v[86:87], off offset:2048
	global_load_dwordx4 v[220:223], v[84:85], off offset:3072
	global_load_dwordx4 v[80:83], v[86:87], off offset:3072
.Llnb_nomod:
	global_load_dwordx4 v[12:15], v[0:1], off
	global_load_dwordx4 v[8:11], v[0:1], off offset:1024
	global_load_dwordx4 v[4:7], v[0:1], off offset:2048
	s_nop 0
	global_load_dwordx4 v[0:3], v[0:1], off offset:3072
	v_pk_add_f32 v[24:25], v[46:47], v[20:21]
	s_mov_b32 s8, 0x800000
	v_pk_add_f32 v[24:25], v[48:49], v[24:25]
	s_nop 0
	v_pk_add_f32 v[24:25], v[22:23], v[24:25]
	s_nop 0
	v_add_f32_e32 v25, 0, v25
	v_add_f32_e32 v26, v24, v25
	v_pk_add_f32 v[24:25], v[40:41], v[16:17]
	s_nop 0
	v_pk_add_f32 v[24:25], v[42:43], v[24:25]
	s_nop 0
	v_pk_add_f32 v[24:25], v[18:19], v[24:25]
	s_nop 0
	v_add_f32_e32 v25, v25, v26
	v_add_f32_e32 v24, v24, v25
	s_nop 1
	v_add_f32_dpp v24, v24, v24 quad_perm:[1,0,3,2] row_mask:0xf bank_mask:0xf bound_ctrl:1
	s_nop 1
	v_add_f32_dpp v24, v24, v24 quad_perm:[2,3,0,1] row_mask:0xf bank_mask:0xf bound_ctrl:1
	s_nop 1
	v_add_f32_dpp v24, v24, v24 row_half_mirror row_mask:0xf bank_mask:0xf bound_ctrl:1
	s_nop 1
	v_add_f32_dpp v24, v24, v24 row_mirror row_mask:0xf bank_mask:0xf bound_ctrl:1
	s_nop 0
	v_readlane_b32 s16, v24, 16
	v_readlane_b32 s17, v24, 48
	v_readlane_b32 s14, v24, 0
	v_readlane_b32 s15, v24, 32
	v_mov_b32_e32 v24, s16
	v_mov_b32_e32 v25, s17
	v_pk_add_f32 v[24:25], s[14:15], v[24:25]
	s_nop 0
	v_add_f32_e32 v24, v24, v25
	v_fmac_f32_e32 v21, 0xba800000, v24
	v_fmac_f32_e32 v20, 0xba800000, v24
	v_fmac_f32_e32 v47, 0xba800000, v24
	v_fmac_f32_e32 v46, 0xba800000, v24
	v_mov_b32_e32 v44, v21
	v_mov_b32_e32 v45, v20
	v_fmac_f32_e32 v49, 0xba800000, v24
	v_fmac_f32_e32 v48, 0xba800000, v24
	v_mov_b32_e32 v26, v47
	v_mov_b32_e32 v27, v46
	v_pk_mul_f32 v[44:45], v[44:45], v[44:45]
	v_fmac_f32_e32 v23, 0xba800000, v24
	v_fmac_f32_e32 v22, 0xba800000, v24
	v_pk_fma_f32 v[26:27], v[26:27], v[26:27], v[44:45]
	v_mov_b32_e32 v44, v49
	v_mov_b32_e32 v45, v48
	v_pk_fma_f32 v[26:27], v[44:45], v[44:45], v[26:27]
	v_mov_b32_e32 v44, v23
	v_mov_b32_e32 v45, v22
	v_fmac_f32_e32 v17, 0xba800000, v24
	v_fmac_f32_e32 v16, 0xba800000, v24
	v_pk_fma_f32 v[26:27], v[44:45], v[44:45], v[26:27]
	v_fmac_f32_e32 v41, 0xba800000, v24
	v_fmac_f32_e32 v40, 0xba800000, v24
	v_pk_mul_f32 v[44:45], v[16:17], v[16:17]
	v_fmac_f32_e32 v43, 0xba800000, v24
	v_fmac_f32_e32 v42, 0xba800000, v24
	v_pk_fma_f32 v[44:45], v[40:41], v[40:41], v[44:45]
	v_fmac_f32_e32 v19, 0xba800000, v24
	v_fmac_f32_e32 v18, 0xba800000, v24
	v_pk_fma_f32 v[44:45], v[42:43], v[42:43], v[44:45]
	v_add_f32_e32 v25, v26, v27
	v_pk_fma_f32 v[44:45], v[18:19], v[18:19], v[44:45]
	s_nop 0
	v_add_f32_e32 v25, v45, v25
	v_add_f32_e32 v25, v44, v25
	s_nop 1
	v_add_f32_dpp v25, v25, v25 quad_perm:[1,0,3,2] row_mask:0xf bank_mask:0xf bound_ctrl:1
	s_nop 1
	v_add_f32_dpp v25, v25, v25 quad_perm:[2,3,0,1] row_mask:0xf bank_mask:0xf bound_ctrl:1
	s_nop 1
	v_add_f32_dpp v25, v25, v25 row_half_mirror row_mask:0xf bank_mask:0xf bound_ctrl:1
	s_nop 1
	v_add_f32_dpp v25, v25, v25 row_mirror row_mask:0xf bank_mask:0xf bound_ctrl:1
	s_nop 0
	v_readlane_b32 s16, v25, 16
	v_readlane_b32 s17, v25, 48
	v_readlane_b32 s14, v25, 0
	v_readlane_b32 s15, v25, 32
	v_mov_b32_e32 v26, s16
	v_mov_b32_e32 v27, s17
	v_pk_add_f32 v[26:27], s[14:15], v[26:27]
	s_nop 0
	v_add_f32_e32 v25, v26, v27
	v_fmamk_f32 v25, v25, 0x3a800000, v232
	v_mul_f32_e32 v26, 0x4b800000, v25
	v_cmp_gt_f32_e32 vcc, s8, v25
	s_nop 1
	v_cndmask_b32_e32 v25, v25, v26, vcc
	v_rsq_f32_e32 v25, v25
	s_nop 0
	v_mul_f32_e32 v26, 0x45800000, v25
	v_cndmask_b32_e32 v44, v25, v26, vcc
	s_waitcnt vmcnt(4)
	s_and_saveexec_b64 s[34:35], s[2:3]
	s_cbranch_execz .LBB0_1912
	s_add_u32 s14, s92, s1
	v_mul_f32_e32 v24, 0x3a800000, v24
	s_addc_u32 s15, s93, s10
	v_mov_b32_e32 v25, v44
	global_store_dwordx2 v51, v[24:25], s[14:15]
.LBB0_1912:
	s_or_b64 exec, exec, s[34:35]
	v_mov_b32_e32 v24, v47
	v_mov_b32_e32 v25, v21
	v_mov_b32_e32 v26, v49
	v_mov_b32_e32 v27, v23
	v_pk_mul_f32 v[58:59], v[26:27], v[44:45] op_sel_hi:[1,0]
	v_pk_mul_f32 v[60:61], v[24:25], v[44:45] op_sel_hi:[1,0]
	v_readlane_b32 s8, v254, 31
	v_readlane_b32 s9, v254, 32
	s_andn2_b64 vcc, exec, s[8:9]
	v_pk_fma_f32 v[26:27], v[58:59], v[166:167], v[182:183]
	v_cndmask_b32_e64 v21, 0, 1, s[8:9]
	v_pk_fma_f32 v[24:25], v[60:61], v[164:165], v[180:181]
	v_cmp_ne_u32_e64 s[38:39], 1, v21
	s_cbranch_vccnz .LBB0_1914
	global_store_dwordx4 v[38:39], v[24:27], off offset:-2048
.LBB0_1914:
	s_add_i32 s15, s26, 0xffffc000
	s_lshr_b32 s15, s15, 12
	s_ashr_i32 s14, s26, 13
	s_add_i32 s15, s15, 2
	s_cmpk_lt_i32 s26, 0x4000
	s_cselect_b32 s14, s14, s15
	v_readlane_b32 s8, v255, 2
	s_add_i32 s14, s14, s8
	s_mul_i32 s14, s14, 9
	s_ashr_i32 s15, s14, 31
	s_lshl_b64 s[34:35], s[14:15], 12
	s_add_u32 s26, s34, 0x1000
	v_cndmask_b32_e64 v21, 0, 1, s[70:71]
	s_addc_u32 s27, s35, 0
	v_cmp_ne_u32_e64 s[40:41], 1, v21
	s_andn2_b64 vcc, exec, s[70:71]
	s_cbranch_vccnz .LBB0_1916
	s_nop 0
	v_pk_add_f32 v[60:61], v[226:227], 1.0 op_sel_hi:[1,0]
	v_pk_add_f32 v[58:59], v[224:225], 1.0 op_sel_hi:[1,0]
	v_pk_fma_f32 v[26:27], v[26:27], v[60:61], v[210:211]
	v_pk_fma_f32 v[24:25], v[24:25], v[58:59], v[208:209]
	s_nop 0
	v_cvt_pk_bf16_f32 v24, v24, v25
	v_cvt_pk_bf16_f32 v25, v26, v27
	v_lshl_add_u64 v[26:27], s[92:93], 0, v[36:37]
	v_add_co_u32_e32 v26, vcc, 0x2c00000, v26
	s_nop 1
	v_addc_co_u32_e32 v27, vcc, 0, v27, vcc
	global_store_dwordx2 v[26:27], v[24:25], off
.LBB0_1916:
	v_mov_b32_e32 v47, v20
	v_mov_b32_e32 v20, v44
	v_mov_b32_e32 v21, v44
	v_mov_b32_e32 v49, v22
	v_pk_mul_f32 v[48:49], v[48:49], v[20:21]
	v_mov_b32_e32 v45, v44
	v_pk_mul_f32 v[46:47], v[46:47], v[44:45]
	s_and_b64 vcc, exec, s[38:39]
	v_pk_fma_f32 v[22:23], v[48:49], v[170:171], v[198:199]
	v_pk_fma_f32 v[20:21], v[46:47], v[168:169], v[196:197]
	s_cbranch_vccnz .LBB0_1918
	global_store_dwordx4 v[38:39], v[20:23], off offset:-1024
.LBB0_1918:
	s_and_b64 vcc, exec, s[40:41]
	s_cbranch_vccnz .LBB0_1920
	s_nop 0
	v_pk_add_f32 v[48:49], v[230:231], 1.0 op_sel_hi:[1,0]
	v_pk_add_f32 v[46:47], v[228:229], 1.0 op_sel_hi:[1,0]
	v_pk_fma_f32 v[22:23], v[22:23], v[48:49], v[214:215]
	v_pk_fma_f32 v[20:21], v[20:21], v[46:47], v[212:213]
	s_nop 0
	v_cvt_pk_bf16_f32 v20, v20, v21
	v_cvt_pk_bf16_f32 v21, v22, v23
	v_lshl_add_u64 v[22:23], s[92:93], 0, v[36:37]
	v_add_co_u32_e32 v22, vcc, 0x2c00000, v22
	s_nop 1
	v_addc_co_u32_e32 v23, vcc, 0, v23, vcc
	global_store_dwordx2 v[22:23], v[20:21], off offset:512
.LBB0_1920:
	v_mov_b32_e32 v20, v41
	v_mov_b32_e32 v21, v17
	v_mov_b32_e32 v22, v44
	v_mov_b32_e32 v23, v44
	v_mov_b32_e32 v24, v43
	v_mov_b32_e32 v25, v19
	v_pk_mul_f32 v[46:47], v[24:25], v[22:23]
	v_pk_mul_f32 v[48:49], v[20:21], v[44:45]
	s_and_b64 vcc, exec, s[38:39]
	v_pk_fma_f32 v[22:23], v[46:47], v[174:175], v[202:203]
	v_pk_fma_f32 v[20:21], v[48:49], v[172:173], v[200:201]
	s_cbranch_vccnz .LBB0_1922
	global_store_dwordx4 v[38:39], v[20:23], off
.LBB0_1922:
	s_and_b64 vcc, exec, s[40:41]
	s_cbranch_vccnz .LBB0_1924
	s_nop 0
	v_pk_add_f32 v[48:49], v[78:79], 1.0 op_sel_hi:[1,0]
	v_pk_add_f32 v[46:47], v[76:77], 1.0 op_sel_hi:[1,0]
	v_pk_fma_f32 v[22:23], v[22:23], v[48:49], v[218:219]
	v_pk_fma_f32 v[20:21], v[20:21], v[46:47], v[216:217]
	s_nop 0
	v_cvt_pk_bf16_f32 v20, v20, v21
	v_cvt_pk_bf16_f32 v21, v22, v23
	v_lshl_add_u64 v[22:23], s[92:93], 0, v[36:37]
	v_add_co_u32_e32 v22, vcc, 0x2c00000, v22
	s_nop 1
	v_addc_co_u32_e32 v23, vcc, 0, v23, vcc
	global_store_dwordx2 v[22:23], v[20:21], off offset:1024
.LBB0_1924:
	v_mov_b32_e32 v41, v16
	v_mov_b32_e32 v16, v44
	v_mov_b32_e32 v17, v44
	v_mov_b32_e32 v43, v18
	v_pk_mul_f32 v[24:25], v[42:43], v[16:17]
	v_pk_mul_f32 v[26:27], v[40:41], v[44:45]
	s_and_b64 vcc, exec, s[38:39]
	v_pk_fma_f32 v[18:19], v[24:25], v[178:179], v[206:207]
	v_pk_fma_f32 v[16:17], v[26:27], v[176:177], v[204:205]
	s_cbranch_vccnz .LBB0_1926
	global_store_dwordx4 v[38:39], v[16:19], off offset:1024
.LBB0_1926:
	s_and_b64 vcc, exec, s[40:41]
	s_cbranch_vccnz .LBB0_1909
	s_nop 0
	v_pk_add_f32 v[26:27], v[82:83], 1.0 op_sel_hi:[1,0]
	v_pk_add_f32 v[24:25], v[80:81], 1.0 op_sel_hi:[1,0]
	v_pk_fma_f32 v[18:19], v[18:19], v[26:27], v[222:223]
	v_pk_fma_f32 v[16:17], v[16:17], v[24:25], v[220:221]
	s_nop 0
	v_cvt_pk_bf16_f32 v16, v16, v17
	v_cvt_pk_bf16_f32 v17, v18, v19
	v_lshl_add_u64 v[18:19], s[92:93], 0, v[36:37]
	v_add_co_u32_e32 v18, vcc, 0x2c00000, v18
	s_nop 1
	v_addc_co_u32_e32 v19, vcc, 0, v19, vcc
	global_store_dwordx2 v[18:19], v[16:17], off offset:1536
	s_branch .LBB0_1909
